# attention QK^T: K-fragment LDS reads kept 7 deep in a register ring instead of read-wait-MFMA per step
# baseline (speedup 1.0000x reference)
; #define LAS __attribute__((address_space(3)))
; #define ATT_STAGE_LOAD(SRC, IT) do { _Pragma("unroll") for (int i_ = 0; i_ < 12; ++i_) { const int chunk_ = tid + 512 * i_, rr_ = chunk_ >> 4, ch_ = chunk_ & 15, lv_ = (IT).lq0 - 128 + rr_; \
;         u32x4 val_ = {0u, 0u, 0u, 0u}; if (lv_ >= 0) val_ = *(const u32x4*)((SRC) + ((size_t)lv_ * (IT).d + (IT).res) * 1024 + (IT).hh * 128 + ch_ * 8); stg[i_] = val_; } } while (0)
; __device__ __forceinline__ void attn_phase(LAS unsigned char* lds, const bf16* __restrict__ Q, const bf16* __restrict__ Kb, const bf16* __restrict__ Vb, unsigned char* ws, float* PM, int tid, int wave, int lane) {
;     ...
;         ATT_STAGE_LOAD(Vb, I);
;         f32x16 sacc[5];
;         const LAS unsigned char* kb = lds + (32 * wave + r) * KROW + h * 16;
;         const int lkw = I.lq0 - 128 + 32 * wave;
; #pragma unroll
;         for (int i = 0; i < 5; ++i) {
; #pragma unroll
;             for (int e = 0; e < 16; ++e) sacc[i][e] = 0.f;
; #pragma unroll
;             for (int s = 0; s < 8; ++s) { const bf16x8 kf = *(const LAS bf16x8*)(kb + (32 * i) * KROW + 32 * s); sacc[i] = __builtin_amdgcn_mfma_f32_32x32x16_bf16(kf, qf[s], sacc[i], 0, 0, 0); }
;         }
; #pragma unroll
;         for (int e = 0; e < 16; ++e) { const int kv = (e & 3) + 8 * (e >> 2) + 4 * h; if (kv < r) sacc[0][e] = -INFINITY; if (kv > r) sacc[4][e] = -INFINITY; }
; #pragma unroll
;         for (int i = 0; i < 4; ++i) if (lkw + 32 * i < 0) {
; #pragma unroll
;             for (int e = 0; e < 16; ++e) sacc[i][e] = -INFINITY;
;         }
.LBB0_583:
	s_or_b64 exec, exec, s[0:1]
	v_add_u32_e32 v4, s4, v202
	v_mov_b64_e32 v[2:3], s[96:97]
	v_mad_u64_u32 v[4:5], s[0:1], v4, s3, v[2:3]
	v_lshlrev_b64 v[4:5], 11, v[4:5]
	v_lshl_add_u64 v[4:5], v[0:1], 0, v[4:5]
	global_load_dwordx4 v[100:103], v[4:5], off
	v_add_u32_e32 v4, s4, v203
	v_mad_u64_u32 v[4:5], s[0:1], v4, s3, v[2:3]
	v_lshlrev_b64 v[4:5], 11, v[4:5]
	v_lshl_add_u64 v[4:5], v[0:1], 0, v[4:5]
	global_load_dwordx4 v[104:107], v[4:5], off
	v_add_u32_e32 v4, s4, v204
	v_mad_u64_u32 v[4:5], s[0:1], v4, s3, v[2:3]
	v_lshlrev_b64 v[4:5], 11, v[4:5]
	v_lshl_add_u64 v[4:5], v[0:1], 0, v[4:5]
	global_load_dwordx4 v[112:115], v[4:5], off
	v_add_u32_e32 v4, s4, v205
	v_mad_u64_u32 v[4:5], s[0:1], v4, s3, v[2:3]
	v_lshlrev_b64 v[4:5], 11, v[4:5]
	v_lshl_add_u64 v[4:5], v[0:1], 0, v[4:5]
	global_load_dwordx4 v[128:131], v[4:5], off
	v_add_u32_e32 v4, s4, v206
	v_mad_u64_u32 v[4:5], s[0:1], v4, s3, v[2:3]
	v_lshlrev_b64 v[4:5], 11, v[4:5]
	v_lshl_add_u64 v[4:5], v[0:1], 0, v[4:5]
	global_load_dwordx4 v[148:151], v[4:5], off
	v_add_u32_e32 v4, s4, v207
	v_mad_u64_u32 v[4:5], s[0:1], v4, s3, v[2:3]
	v_lshlrev_b64 v[4:5], 11, v[4:5]
	v_lshl_add_u64 v[4:5], v[0:1], 0, v[4:5]
	global_load_dwordx4 v[152:155], v[4:5], off
	v_add_u32_e32 v4, s4, v208
	v_mad_u64_u32 v[4:5], s[0:1], v4, s3, v[2:3]
	v_lshlrev_b64 v[4:5], 11, v[4:5]
	v_lshl_add_u64 v[4:5], v[0:1], 0, v[4:5]
	global_load_dwordx4 v[156:159], v[4:5], off
	v_add_u32_e32 v4, s4, v209
	v_mad_u64_u32 v[2:3], s[0:1], v4, s3, v[2:3]
	v_lshlrev_b64 v[2:3], 11, v[2:3]
	v_lshl_add_u64 v[0:1], v[0:1], 0, v[2:3]
	global_load_dwordx4 v[160:163], v[0:1], off
	ds_read_b128 v[168:171], v221
	ds_read_b128 v[172:175], v221 offset:32
	ds_read_b128 v[176:179], v221 offset:64
	ds_read_b128 v[180:183], v221 offset:96
	ds_read_b128 v[232:235], v221 offset:128
	ds_read_b128 v[236:239], v221 offset:160
	ds_read_b128 v[240:243], v221 offset:192
	s_waitcnt vmcnt(15)
	s_waitcnt lgkmcnt(6)
	v_mfma_f32_32x32x16_bf16 v[32:47], v[168:171], v[108:111], 0
	ds_read_b128 v[168:171], v221 offset:224
	v_readlane_b32 s0, v245, 48
	v_readlane_b32 s1, v245, 49
	s_add_i32 s4, s4, s33
	s_cmp_gt_i32 s4, -1
	s_waitcnt vmcnt(14)
	s_waitcnt lgkmcnt(6)
	v_mfma_f32_32x32x16_bf16 v[32:47], v[172:175], v[116:119], v[32:47]
	ds_read_b128 v[172:175], v221 offset:8704
	s_cselect_b64 vcc, -1, 0
	s_cmpk_gt_i32 s4, 0xffdf
	s_mov_b32 s94, s96
	s_mov_b32 s95, s3
	s_mov_b32 s5, s93
	s_mov_b32 s92, s84
	s_waitcnt vmcnt(13)
	s_waitcnt lgkmcnt(6)
	v_mfma_f32_32x32x16_bf16 v[32:47], v[176:179], v[120:123], v[32:47]
	ds_read_b128 v[176:179], v221 offset:8736
	s_waitcnt vmcnt(12)
	s_waitcnt lgkmcnt(6)
	v_mfma_f32_32x32x16_bf16 v[32:47], v[180:183], v[124:127], v[32:47]
	ds_read_b128 v[180:183], v221 offset:8768
	s_waitcnt vmcnt(11)
	s_waitcnt lgkmcnt(6)
	v_mfma_f32_32x32x16_bf16 v[32:47], v[232:235], v[132:135], v[32:47]
	ds_read_b128 v[232:235], v221 offset:8800
	s_waitcnt vmcnt(10)
	s_waitcnt lgkmcnt(6)
	v_mfma_f32_32x32x16_bf16 v[32:47], v[236:239], v[136:139], v[32:47]
	ds_read_b128 v[236:239], v221 offset:8832
	s_waitcnt vmcnt(9)
	s_waitcnt lgkmcnt(6)
	v_mfma_f32_32x32x16_bf16 v[32:47], v[240:243], v[140:143], v[32:47]
	ds_read_b128 v[240:243], v221 offset:8864
	s_waitcnt vmcnt(8)
	s_waitcnt lgkmcnt(6)
	v_mfma_f32_32x32x16_bf16 v[32:47], v[168:171], v[144:147], v[32:47]
	ds_read_b128 v[168:171], v221 offset:8896
	s_waitcnt lgkmcnt(6)
	v_mfma_f32_32x32x16_bf16 v[0:15], v[172:175], v[108:111], 0
	ds_read_b128 v[172:175], v221 offset:8928
	s_nop 8
	v_cndmask_b32_e64 v32, v32, v231, s[6:7]
	v_cndmask_b32_e64 v34, v34, v231, s[12:13]
	v_cndmask_b32_e64 v35, v35, v231, s[16:17]
	v_cndmask_b32_e64 v36, v36, v231, s[26:27]
	v_cndmask_b32_e64 v37, v37, v231, s[74:75]
	v_cndmask_b32_e64 v38, v38, v231, s[28:29]
	v_cndmask_b32_e64 v39, v39, v231, s[34:35]
	s_waitcnt lgkmcnt(6)
	v_mfma_f32_32x32x16_bf16 v[0:15], v[176:179], v[116:119], v[0:15]
	ds_read_b128 v[176:179], v221 offset:17408
	v_cndmask_b32_e64 v40, v40, v231, s[38:39]
	v_cndmask_b32_e64 v41, v41, v231, s[42:43]
	v_cndmask_b32_e64 v42, v42, v231, s[46:47]
	v_cndmask_b32_e64 v43, v43, v231, s[50:51]
	v_cndmask_b32_e64 v44, v44, v231, s[54:55]
	v_cndmask_b32_e64 v45, v45, v231, s[58:59]
	s_waitcnt lgkmcnt(6)
	v_mfma_f32_32x32x16_bf16 v[0:15], v[180:183], v[120:123], v[0:15]
	ds_read_b128 v[180:183], v221 offset:17440
	v_cndmask_b32_e64 v46, v46, v231, s[62:63]
	v_cndmask_b32_e64 v47, v47, v231, s[66:67]
	v_cndmask_b32_e32 v47, v231, v47, vcc
	v_cndmask_b32_e32 v46, v231, v46, vcc
	v_cndmask_b32_e32 v45, v231, v45, vcc
	v_cndmask_b32_e32 v44, v231, v44, vcc
	s_waitcnt lgkmcnt(6)
	v_mfma_f32_32x32x16_bf16 v[0:15], v[232:235], v[124:127], v[0:15]
	ds_read_b128 v[232:235], v221 offset:17472
	v_cndmask_b32_e32 v43, v231, v43, vcc
	v_cndmask_b32_e32 v42, v231, v42, vcc
	v_cndmask_b32_e32 v41, v231, v41, vcc
	v_cndmask_b32_e32 v40, v231, v40, vcc
	v_cndmask_b32_e32 v39, v231, v39, vcc
	v_cndmask_b32_e32 v38, v231, v38, vcc
	s_waitcnt lgkmcnt(6)
	v_mfma_f32_32x32x16_bf16 v[0:15], v[236:239], v[132:135], v[0:15]
	ds_read_b128 v[236:239], v221 offset:17504
	v_cndmask_b32_e32 v37, v231, v37, vcc
	v_cndmask_b32_e32 v36, v231, v36, vcc
	v_cndmask_b32_e32 v35, v231, v35, vcc
	v_cndmask_b32_e32 v34, v231, v34, vcc
	v_cndmask_b32_e32 v32, v231, v32, vcc
	s_waitcnt lgkmcnt(6)
	v_mfma_f32_32x32x16_bf16 v[0:15], v[240:243], v[136:139], v[0:15]
	ds_read_b128 v[240:243], v221 offset:17536
	s_waitcnt lgkmcnt(6)
	v_mfma_f32_32x32x16_bf16 v[0:15], v[168:171], v[140:143], v[0:15]
	ds_read_b128 v[168:171], v221 offset:17568
	s_waitcnt lgkmcnt(6)
	v_mfma_f32_32x32x16_bf16 v[0:15], v[172:175], v[144:147], v[0:15]
	ds_read_b128 v[172:175], v221 offset:17600
	s_waitcnt lgkmcnt(6)
; #define LAS __attribute__((address_space(3)))
; #define LBAR() do { asm volatile("s_waitcnt lgkmcnt(0)" ::: "memory"); __builtin_amdgcn_s_barrier(); asm volatile("" ::: "memory"); } while (0)
; #define ATT_STAGE_WRITE(ROWB) do { _Pragma("unroll") for (int i_ = 0; i_ < 12; ++i_) { const int chunk_ = tid + 512 * i_, rr_ = chunk_ >> 4, ch_ = chunk_ & 15; *(LAS u32x4*)(lds + rr_ * (ROWB) + ch_ * 16) = stg[i_]; } } while (0)
; __device__ __forceinline__ void attn_phase(LAS unsigned char* lds, const bf16* __restrict__ Q, const bf16* __restrict__ Kb, const bf16* __restrict__ Vb, unsigned char* ws, float* PM, int tid, int wave, int lane) {
;     ...
;         for (int i = 0; i < 5; ++i) {
; #pragma unroll
;             for (int e = 0; e < 16; ++e) sacc[i][e] = 0.f;
; #pragma unroll
;             for (int s = 0; s < 8; ++s) { const bf16x8 kf = *(const LAS bf16x8*)(kb + (32 * i) * KROW + 32 * s); sacc[i] = __builtin_amdgcn_mfma_f32_32x32x16_bf16(kf, qf[s], sacc[i], 0, 0, 0); }
;         }
; #pragma unroll
;         for (int e = 0; e < 16; ++e) { const int kv = (e & 3) + 8 * (e >> 2) + 4 * h; if (kv < r) sacc[0][e] = -INFINITY; if (kv > r) sacc[4][e] = -INFINITY; }
; #pragma unroll
;         for (int i = 0; i < 4; ++i) if (lkw + 32 * i < 0) {
; #pragma unroll
;             for (int e = 0; e < 16; ++e) sacc[i][e] = -INFINITY;
;         }
;         float m = sacc[4][0];
; #pragma unroll
;         for (int i = 0; i < 5; ++i)
; #pragma unroll
;             for (int e = 0; e < 16; ++e) m = fmaxf(m, sacc[i][e]);
;         { auto rr = __builtin_amdgcn_permlane32_swap(__float_as_uint(m), __float_as_uint(m), false, false); m = fmaxf(__uint_as_float(rr[0]), __uint_as_float(rr[1])); }
;     ...
;         LBAR();
;         ATT_STAGE_WRITE(VROW);
;         LBAR();
	v_mfma_f32_32x32x16_bf16 v[16:31], v[176:179], v[108:111], 0
	ds_read_b128 v[176:179], v221 offset:17632
	s_waitcnt lgkmcnt(6)
	v_mfma_f32_32x32x16_bf16 v[16:31], v[180:183], v[116:119], v[16:31]
	ds_read_b128 v[180:183], v221 offset:26112
	s_waitcnt lgkmcnt(6)
	v_mfma_f32_32x32x16_bf16 v[16:31], v[232:235], v[120:123], v[16:31]
	ds_read_b128 v[232:235], v221 offset:26144
	s_waitcnt lgkmcnt(6)
	v_mfma_f32_32x32x16_bf16 v[16:31], v[236:239], v[124:127], v[16:31]
	ds_read_b128 v[236:239], v221 offset:26176
	s_waitcnt lgkmcnt(6)
	v_mfma_f32_32x32x16_bf16 v[16:31], v[240:243], v[132:135], v[16:31]
	ds_read_b128 v[240:243], v221 offset:26208
	s_waitcnt lgkmcnt(6)
	v_mfma_f32_32x32x16_bf16 v[16:31], v[168:171], v[136:139], v[16:31]
	ds_read_b128 v[168:171], v221 offset:26240
	s_waitcnt lgkmcnt(6)
	v_mfma_f32_32x32x16_bf16 v[16:31], v[172:175], v[140:143], v[16:31]
	ds_read_b128 v[172:175], v221 offset:26272
	s_waitcnt lgkmcnt(6)
	v_mfma_f32_32x32x16_bf16 v[16:31], v[176:179], v[144:147], v[16:31]
	ds_read_b128 v[176:179], v221 offset:26304
	s_waitcnt lgkmcnt(6)
	v_mfma_f32_32x32x16_bf16 v[48:63], v[180:183], v[108:111], 0
	ds_read_b128 v[180:183], v221 offset:26336
	s_waitcnt lgkmcnt(6)
	v_mfma_f32_32x32x16_bf16 v[48:63], v[232:235], v[116:119], v[48:63]
	ds_read_b128 v[232:235], v221 offset:34816
	s_waitcnt lgkmcnt(6)
	v_mfma_f32_32x32x16_bf16 v[48:63], v[236:239], v[120:123], v[48:63]
	ds_read_b128 v[236:239], v221 offset:34848
	s_waitcnt lgkmcnt(6)
	v_mfma_f32_32x32x16_bf16 v[48:63], v[240:243], v[124:127], v[48:63]
	ds_read_b128 v[240:243], v221 offset:34880
	s_waitcnt lgkmcnt(6)
	v_mfma_f32_32x32x16_bf16 v[48:63], v[168:171], v[132:135], v[48:63]
	ds_read_b128 v[168:171], v221 offset:34912
	s_waitcnt lgkmcnt(6)
	v_mfma_f32_32x32x16_bf16 v[48:63], v[172:175], v[136:139], v[48:63]
	ds_read_b128 v[172:175], v221 offset:34944
	s_waitcnt lgkmcnt(6)
	v_mfma_f32_32x32x16_bf16 v[48:63], v[176:179], v[140:143], v[48:63]
	ds_read_b128 v[176:179], v221 offset:34976
	s_waitcnt lgkmcnt(6)
	v_mfma_f32_32x32x16_bf16 v[48:63], v[180:183], v[144:147], v[48:63]
	ds_read_b128 v[180:183], v221 offset:35008
	s_waitcnt lgkmcnt(6)
	v_mfma_f32_32x32x16_bf16 v[64:79], v[232:235], v[108:111], 0
	ds_read_b128 v[232:235], v221 offset:35040
	s_waitcnt lgkmcnt(6)
	v_mfma_f32_32x32x16_bf16 v[64:79], v[236:239], v[116:119], v[64:79]
	s_waitcnt lgkmcnt(5)
	v_mfma_f32_32x32x16_bf16 v[64:79], v[240:243], v[120:123], v[64:79]
	s_waitcnt lgkmcnt(4)
	v_mfma_f32_32x32x16_bf16 v[64:79], v[168:171], v[124:127], v[64:79]
	s_waitcnt lgkmcnt(3)
	v_mfma_f32_32x32x16_bf16 v[64:79], v[172:175], v[132:135], v[64:79]
	s_waitcnt lgkmcnt(2)
	v_mfma_f32_32x32x16_bf16 v[64:79], v[176:179], v[136:139], v[64:79]
	s_waitcnt lgkmcnt(1)
	v_mfma_f32_32x32x16_bf16 v[64:79], v[180:183], v[140:143], v[64:79]
	s_waitcnt lgkmcnt(0)
	s_barrier
	ds_write_b128 v222, v[84:87]
	ds_write_b128 v223, v[88:91]
	ds_write_b128 v222, v[92:95] offset:20480
	ds_write_b128 v224, v[96:99]
	s_waitcnt vmcnt(7)
	ds_write_b128 v222, v[100:103] offset:40960
	s_waitcnt vmcnt(6)
	ds_write_b128 v225, v[104:107]
	s_waitcnt vmcnt(5)
	ds_write_b128 v222, v[112:115] offset:61440
	s_waitcnt vmcnt(4)
	ds_write_b128 v226, v[128:131]
	s_waitcnt vmcnt(3)
	ds_write_b128 v227, v[148:151] offset:61440
	s_waitcnt vmcnt(2)
	ds_write_b128 v228, v[152:155]
	s_waitcnt vmcnt(1)
	ds_write_b128 v229, v[156:159] offset:61440
	s_waitcnt vmcnt(0)
	ds_write_b128 v230, v[160:163]
	s_waitcnt lgkmcnt(0)
	s_barrier
	s_waitcnt lgkmcnt(12)
	v_mfma_f32_32x32x16_bf16 v[64:79], v[232:235], v[144:147], v[64:79]
	s_nop 11
	v_cndmask_b32_e64 v81, v64, v231, s[0:1]
	v_readlane_b32 s0, v245, 50
	v_readlane_b32 s1, v245, 51
	v_cndmask_b32_e64 v81, v81, v64, s[6:7]
	v_cndmask_b32_e64 v167, v70, v231, s[30:31]
	v_cndmask_b32_e64 v33, v33, v231, s[0:1]
	v_cndmask_b32_e32 v33, v231, v33, vcc
	s_cselect_b64 vcc, -1, 0
	v_cndmask_b32_e32 v172, v231, v4, vcc
	v_max3_f32 v4, v81, v32, v33
	v_max3_f32 v4, v4, v34, v35
	v_max3_f32 v4, v4, v36, v37
	v_max3_f32 v4, v4, v38, v39
	v_max3_f32 v4, v4, v40, v41
	v_max3_f32 v4, v4, v42, v43
	v_max3_f32 v4, v4, v44, v45
	v_cndmask_b32_e32 v1, v231, v1, vcc
	v_cndmask_b32_e32 v0, v231, v0, vcc
	v_max3_f32 v4, v4, v46, v47
	v_cndmask_b32_e32 v3, v231, v3, vcc
	v_cndmask_b32_e32 v2, v231, v2, vcc
	v_max3_f32 v4, v4, v0, v1
	v_cndmask_b32_e32 v171, v231, v5, vcc
	v_max3_f32 v4, v4, v2, v3
	v_cndmask_b32_e32 v169, v231, v7, vcc
	v_cndmask_b32_e32 v170, v231, v6, vcc
	v_max3_f32 v4, v4, v172, v171
	v_cndmask_b32_e64 v168, v71, v231, s[36:37]
	v_cndmask_b32_e32 v70, v231, v9, vcc
	v_cndmask_b32_e32 v71, v231, v8, vcc
	v_max3_f32 v4, v4, v170, v169
	v_cndmask_b32_e64 v165, v68, v231, s[72:73]
	v_cndmask_b32_e64 v166, v69, v231, s[78:79]
	v_cndmask_b32_e32 v68, v231, v11, vcc
	v_cndmask_b32_e32 v69, v231, v10, vcc
	v_max3_f32 v4, v4, v71, v70
	v_cndmask_b32_e64 v83, v66, v231, s[14:15]
	v_cndmask_b32_e64 v164, v67, v231, s[24:25]
	v_cndmask_b32_e32 v66, v231, v13, vcc
	v_cndmask_b32_e32 v67, v231, v12, vcc
	s_cmpk_gt_i32 s4, 0xffbf
	v_max3_f32 v4, v4, v69, v68
	v_cndmask_b32_e64 v82, v231, v65, s[6:7]
	v_cndmask_b32_e32 v64, v231, v15, vcc
	v_cndmask_b32_e32 v65, v231, v14, vcc
	s_cselect_b64 vcc, -1, 0
	v_max3_f32 v4, v4, v67, v66
	v_cndmask_b32_e32 v233, v231, v17, vcc
	v_cndmask_b32_e32 v234, v231, v16, vcc
	v_max3_f32 v4, v4, v65, v64
	v_cndmask_b32_e32 v197, v231, v19, vcc
	v_cndmask_b32_e32 v232, v231, v18, vcc
	v_max3_f32 v4, v4, v234, v233
	v_cndmask_b32_e32 v183, v231, v21, vcc
	v_cndmask_b32_e32 v195, v231, v20, vcc
	v_max3_f32 v4, v4, v232, v197
	v_cndmask_b32_e32 v181, v231, v23, vcc
	v_cndmask_b32_e32 v182, v231, v22, vcc
; __device__ __forceinline__ unsigned pk2(float lo, float hi) { f32x2_t v = {lo, hi}; bf16x2_t b = __builtin_convertvector(v, bf16x2_t); return __builtin_bit_cast(unsigned, b); }
; __device__ __forceinline__ void attn_phase(LAS unsigned char* lds, const bf16* __restrict__ Q, const bf16* __restrict__ Kb, const bf16* __restrict__ Vb, unsigned char* ws, float* PM, int tid, int wave, int lane) {
;     ...
;         float m = sacc[4][0];
; #pragma unroll
;         for (int i = 0; i < 5; ++i)
; #pragma unroll
;             for (int e = 0; e < 16; ++e) m = fmaxf(m, sacc[i][e]);
;         { auto rr = __builtin_amdgcn_permlane32_swap(__float_as_uint(m), __float_as_uint(m), false, false); m = fmaxf(__uint_as_float(rr[0]), __uint_as_float(rr[1])); }
;         float l = 0.f; u32x4 pw[5][2];
; #pragma unroll
;         for (int i = 0; i < 5; ++i) {
; #pragma unroll
;             for (int e = 0; e < 16; ++e) { sacc[i][e] = __builtin_amdgcn_exp2f(sacc[i][e] - m); l += sacc[i][e]; }
; #pragma unroll
;             for (int s2 = 0; s2 < 2; ++s2) { pw[i][s2].x = pk2(sacc[i][8 * s2], sacc[i][8 * s2 + 1]); pw[i][s2].y = pk2(sacc[i][8 * s2 + 2], sacc[i][8 * s2 + 3]); pw[i][s2].z = pk2(sacc[i][8 * s2 + 4], sacc[i][8 * s2 + 5]); pw[i][s2].w = pk2(sacc[i][8 * s2 + 6], sacc[i][8 * s2 + 7]); }
;         }
;         { auto rr = __builtin_amdgcn_permlane32_swap(__float_as_uint(l), __float_as_uint(l), false, false); l = __uint_as_float(rr[0]) + __uint_as_float(rr[1]); }
	v_max3_f32 v4, v4, v195, v183
	v_cndmask_b32_e32 v179, v231, v25, vcc
	v_cndmask_b32_e32 v180, v231, v24, vcc
	v_max3_f32 v4, v4, v182, v181
	v_cndmask_b32_e32 v177, v231, v27, vcc
	v_cndmask_b32_e32 v178, v231, v26, vcc
	v_max3_f32 v4, v4, v180, v179
	v_cndmask_b32_e32 v175, v231, v29, vcc
	v_cndmask_b32_e32 v176, v231, v28, vcc
	s_cmpk_gt_i32 s4, 0xff9f
	v_max3_f32 v4, v4, v178, v177
	v_cndmask_b32_e32 v173, v231, v31, vcc
	v_cndmask_b32_e32 v174, v231, v30, vcc
	s_cselect_b64 vcc, -1, 0
	v_max3_f32 v4, v4, v176, v175
	v_cndmask_b32_e32 v237, v231, v61, vcc
	v_cndmask_b32_e32 v238, v231, v60, vcc
	v_cndmask_b32_e32 v61, v231, v57, vcc
	v_cndmask_b32_e32 v60, v231, v56, vcc
	v_cndmask_b32_e32 v57, v231, v53, vcc
	v_cndmask_b32_e32 v56, v231, v52, vcc
	v_cndmask_b32_e32 v53, v231, v49, vcc
	v_cndmask_b32_e32 v52, v231, v48, vcc
	v_max3_f32 v4, v4, v174, v173
	v_cndmask_b32_e32 v235, v231, v63, vcc
	v_cndmask_b32_e32 v236, v231, v62, vcc
	v_cndmask_b32_e32 v63, v231, v59, vcc
	v_cndmask_b32_e32 v62, v231, v58, vcc
	v_cndmask_b32_e32 v59, v231, v55, vcc
	v_cndmask_b32_e32 v58, v231, v54, vcc
	v_cndmask_b32_e32 v55, v231, v51, vcc
	v_cndmask_b32_e32 v54, v231, v50, vcc
	v_max3_f32 v4, v4, v52, v53
	v_max3_f32 v4, v4, v54, v55
	v_max3_f32 v4, v4, v56, v57
	v_max3_f32 v4, v4, v58, v59
	v_max3_f32 v4, v4, v60, v61
	v_max3_f32 v4, v4, v62, v63
	v_max3_f32 v4, v4, v238, v237
	v_max3_f32 v4, v4, v236, v235
	v_max3_f32 v4, v4, v81, v82
	v_max3_f32 v4, v4, v83, v164
	v_max3_f32 v4, v4, v165, v166
	v_cndmask_b32_e64 v72, v72, v231, s[40:41]
	v_cndmask_b32_e64 v73, v73, v231, s[44:45]
	v_max3_f32 v4, v4, v167, v168
	v_cndmask_b32_e64 v74, v74, v231, s[48:49]
	v_cndmask_b32_e64 v75, v75, v231, s[52:53]
	v_max3_f32 v4, v4, v72, v73
	v_cndmask_b32_e64 v76, v76, v231, s[56:57]
	v_cndmask_b32_e64 v77, v77, v231, s[60:61]
	v_max3_f32 v4, v4, v74, v75
	v_cndmask_b32_e64 v78, v78, v231, s[64:65]
	v_cndmask_b32_e64 v79, v79, v231, s[68:69]
	v_max3_f32 v4, v4, v76, v77
	v_max3_f32 v4, v4, v78, v79
	v_mov_b32_e32 v5, v4
	s_nop 1
	v_permlane32_swap_b32_e32 v4, v5
	v_max_f32_e32 v5, v5, v5
	v_max_f32_e32 v4, v4, v4
	v_max_f32_e32 v196, v4, v5
	v_sub_f32_e32 v4, v32, v196
	v_exp_f32_e32 v4, v4
	v_sub_f32_e32 v5, v33, v196
	v_exp_f32_e32 v5, v5
	v_sub_f32_e32 v6, v34, v196
	v_exp_f32_e32 v6, v6
	v_sub_f32_e32 v7, v35, v196
	v_exp_f32_e32 v7, v7
	v_sub_f32_e32 v8, v36, v196
	v_exp_f32_e32 v8, v8
	v_sub_f32_e32 v9, v37, v196
	v_add_f32_e32 v20, 0, v4
	v_exp_f32_e32 v9, v9
	v_sub_f32_e32 v10, v38, v196
	v_add_f32_e32 v20, v5, v20
	v_exp_f32_e32 v10, v10
	v_sub_f32_e32 v11, v39, v196
	v_add_f32_e32 v20, v6, v20
	v_exp_f32_e32 v11, v11
	v_sub_f32_e32 v12, v40, v196
	v_add_f32_e32 v20, v7, v20
	v_exp_f32_e32 v12, v12
	v_sub_f32_e32 v13, v41, v196
	v_add_f32_e32 v20, v8, v20
	v_exp_f32_e32 v13, v13
	v_sub_f32_e32 v14, v42, v196
	v_add_f32_e32 v20, v9, v20
	v_exp_f32_e32 v14, v14
	v_sub_f32_e32 v15, v43, v196
	v_add_f32_e32 v20, v10, v20
	v_exp_f32_e32 v15, v15
	v_sub_f32_e32 v16, v44, v196
	v_add_f32_e32 v20, v11, v20
	v_exp_f32_e32 v16, v16
	v_sub_f32_e32 v17, v45, v196
	v_add_f32_e32 v20, v12, v20
	v_exp_f32_e32 v17, v17
	v_sub_f32_e32 v18, v46, v196
	v_add_f32_e32 v20, v13, v20
	v_exp_f32_e32 v18, v18
	v_sub_f32_e32 v19, v47, v196
	v_add_f32_e32 v20, v14, v20
	v_exp_f32_e32 v19, v19
	v_add_f32_e32 v20, v15, v20
	v_add_f32_e32 v20, v16, v20
	v_add_f32_e32 v20, v17, v20
	v_add_f32_e32 v20, v18, v20
	v_sub_f32_e32 v0, v0, v196
	v_add_f32_e32 v36, v19, v20
	v_exp_f32_e32 v20, v0
	v_sub_f32_e32 v0, v1, v196
	v_exp_f32_e32 v21, v0
	v_sub_f32_e32 v0, v2, v196
	v_exp_f32_e32 v22, v0
	v_sub_f32_e32 v0, v3, v196
	v_exp_f32_e32 v23, v0
	v_sub_f32_e32 v0, v172, v196
	v_exp_f32_e32 v24, v0
	v_sub_f32_e32 v0, v171, v196
	v_exp_f32_e32 v25, v0
	v_sub_f32_e32 v0, v170, v196
	v_exp_f32_e32 v26, v0
	v_sub_f32_e32 v0, v169, v196
	v_exp_f32_e32 v27, v0
	v_sub_f32_e32 v0, v71, v196
	v_exp_f32_e32 v28, v0
	v_sub_f32_e32 v0, v70, v196
	v_exp_f32_e32 v29, v0
	v_sub_f32_e32 v0, v69, v196
	v_exp_f32_e32 v30, v0
	v_sub_f32_e32 v0, v68, v196
	v_exp_f32_e32 v31, v0
	v_sub_f32_e32 v0, v67, v196
	v_exp_f32_e32 v32, v0
	v_sub_f32_e32 v0, v66, v196
	v_exp_f32_e32 v33, v0
	v_sub_f32_e32 v0, v65, v196
	v_exp_f32_e32 v34, v0
	v_sub_f32_e32 v0, v64, v196
	v_exp_f32_e32 v35, v0
	v_add_f32_e32 v0, v20, v36
	v_add_f32_e32 v0, v21, v0
	v_add_f32_e32 v0, v22, v0
	v_add_f32_e32 v0, v23, v0
	v_add_f32_e32 v0, v24, v0
	v_add_f32_e32 v0, v25, v0
	v_add_f32_e32 v0, v26, v0
	v_add_f32_e32 v0, v27, v0
	v_add_f32_e32 v0, v28, v0
	v_add_f32_e32 v0, v29, v0
	v_add_f32_e32 v0, v30, v0
	v_add_f32_e32 v0, v31, v0
	v_sub_f32_e32 v1, v234, v196
	v_add_f32_e32 v0, v32, v0
	v_exp_f32_e32 v36, v1
	v_sub_f32_e32 v1, v233, v196
	v_add_f32_e32 v0, v33, v0
	v_exp_f32_e32 v37, v1
	v_sub_f32_e32 v1, v232, v196
	v_add_f32_e32 v0, v34, v0
; __device__ __forceinline__ unsigned pk2(float lo, float hi) { f32x2_t v = {lo, hi}; bf16x2_t b = __builtin_convertvector(v, bf16x2_t); return __builtin_bit_cast(unsigned, b); }
; #define LBAR() do { asm volatile("s_waitcnt lgkmcnt(0)" ::: "memory"); __builtin_amdgcn_s_barrier(); asm volatile("" ::: "memory"); } while (0)
; #define ATT_STAGE_LOAD(SRC, IT) do { _Pragma("unroll") for (int i_ = 0; i_ < 12; ++i_) { const int chunk_ = tid + 512 * i_, rr_ = chunk_ >> 4, ch_ = chunk_ & 15, lv_ = (IT).lq0 - 128 + rr_; \
;         u32x4 val_ = {0u, 0u, 0u, 0u}; if (lv_ >= 0) val_ = *(const u32x4*)((SRC) + ((size_t)lv_ * (IT).d + (IT).res) * 1024 + (IT).hh * 128 + ch_ * 8); stg[i_] = val_; } } while (0)
; #define ATT_STAGE_WRITE(ROWB) do { _Pragma("unroll") for (int i_ = 0; i_ < 12; ++i_) { const int chunk_ = tid + 512 * i_, rr_ = chunk_ >> 4, ch_ = chunk_ & 15; *(LAS u32x4*)(lds + rr_ * (ROWB) + ch_ * 16) = stg[i_]; } } while (0)
; #define ATT_QLOAD(IT) do { const size_t qp_ = (size_t)((IT).lq0 + 32 * wave + r) * (IT).d + (IT).res; const bf16* q_ = Q + qp_ * 1024 + (IT).hh * 128 + 8 * h; \
;         _Pragma("unroll") for (int s_ = 0; s_ < 8; ++s_) qf[s_] = *(const bf16x8*)(q_ + 16 * s_); } while (0)
; __device__ __forceinline__ void attn_phase(LAS unsigned char* lds, const bf16* __restrict__ Q, const bf16* __restrict__ Kb, const bf16* __restrict__ Vb, unsigned char* ws, float* PM, int tid, int wave, int lane) {
;     ...
;         for (int i = 0; i < 5; ++i) {
; #pragma unroll
;             for (int e = 0; e < 16; ++e) { sacc[i][e] = __builtin_amdgcn_exp2f(sacc[i][e] - m); l += sacc[i][e]; }
; #pragma unroll
;             for (int s2 = 0; s2 < 2; ++s2) { pw[i][s2].x = pk2(sacc[i][8 * s2], sacc[i][8 * s2 + 1]); pw[i][s2].y = pk2(sacc[i][8 * s2 + 2], sacc[i][8 * s2 + 3]); pw[i][s2].z = pk2(sacc[i][8 * s2 + 4], sacc[i][8 * s2 + 5]); pw[i][s2].w = pk2(sacc[i][8 * s2 + 6], sacc[i][8 * s2 + 7]); }
;         }
;         { auto rr = __builtin_amdgcn_permlane32_swap(__float_as_uint(l), __float_as_uint(l), false, false); l = __uint_as_float(rr[0]) + __uint_as_float(rr[1]); }
;         LBAR();
;         ATT_STAGE_WRITE(VROW);
;         LBAR();
;         const AttnItem C = I;
;         const int nxt = it + (int)gridDim.x; const bool more = nxt < 1536;
;         if (more) { I = attn_decode(nxt); ATT_STAGE_LOAD(Kb, I); ATT_QLOAD(I); }
	v_exp_f32_e32 v38, v1
	v_sub_f32_e32 v1, v197, v196
	v_add_f32_e32 v0, v35, v0
	v_exp_f32_e32 v39, v1
	v_sub_f32_e32 v1, v195, v196
	v_exp_f32_e32 v40, v1
	v_sub_f32_e32 v1, v183, v196
	v_add_f32_e32 v0, v36, v0
	v_exp_f32_e32 v41, v1
	v_sub_f32_e32 v1, v182, v196
	v_add_f32_e32 v0, v37, v0
	v_exp_f32_e32 v42, v1
	v_sub_f32_e32 v1, v181, v196
	v_add_f32_e32 v0, v38, v0
	v_exp_f32_e32 v43, v1
	v_sub_f32_e32 v1, v180, v196
	v_add_f32_e32 v0, v39, v0
	v_exp_f32_e32 v44, v1
	v_sub_f32_e32 v1, v179, v196
	v_add_f32_e32 v0, v40, v0
	v_exp_f32_e32 v45, v1
	v_sub_f32_e32 v1, v178, v196
	v_add_f32_e32 v0, v41, v0
	v_exp_f32_e32 v46, v1
	v_sub_f32_e32 v1, v177, v196
	v_add_f32_e32 v0, v42, v0
	v_exp_f32_e32 v47, v1
	v_sub_f32_e32 v1, v176, v196
	v_add_f32_e32 v0, v43, v0
	v_exp_f32_e32 v48, v1
	v_sub_f32_e32 v1, v175, v196
	v_add_f32_e32 v0, v44, v0
	v_exp_f32_e32 v49, v1
	v_sub_f32_e32 v1, v174, v196
	v_add_f32_e32 v0, v45, v0
	v_exp_f32_e32 v50, v1
	v_sub_f32_e32 v1, v173, v196
	v_add_f32_e32 v0, v46, v0
	v_exp_f32_e32 v51, v1
	v_add_f32_e32 v0, v47, v0
	v_sub_f32_e32 v1, v52, v196
	v_add_f32_e32 v0, v48, v0
	v_exp_f32_e32 v52, v1
	v_sub_f32_e32 v1, v53, v196
	v_add_f32_e32 v0, v49, v0
	v_exp_f32_e32 v53, v1
	v_sub_f32_e32 v1, v54, v196
	v_add_f32_e32 v0, v50, v0
	v_exp_f32_e32 v54, v1
	v_sub_f32_e32 v1, v55, v196
	v_add_f32_e32 v0, v51, v0
	v_exp_f32_e32 v55, v1
	v_sub_f32_e32 v1, v56, v196
	v_exp_f32_e32 v56, v1
	v_sub_f32_e32 v1, v57, v196
	v_add_f32_e32 v0, v52, v0
	v_exp_f32_e32 v57, v1
	v_sub_f32_e32 v1, v58, v196
	v_add_f32_e32 v0, v53, v0
	v_exp_f32_e32 v58, v1
	v_sub_f32_e32 v1, v59, v196
	v_add_f32_e32 v0, v54, v0
	v_exp_f32_e32 v59, v1
	v_sub_f32_e32 v1, v60, v196
	v_add_f32_e32 v0, v55, v0
	v_exp_f32_e32 v60, v1
	v_sub_f32_e32 v1, v61, v196
	v_add_f32_e32 v0, v56, v0
	v_exp_f32_e32 v61, v1
	v_sub_f32_e32 v1, v62, v196
	v_add_f32_e32 v0, v57, v0
	v_exp_f32_e32 v62, v1
	v_sub_f32_e32 v1, v63, v196
	v_add_f32_e32 v0, v58, v0
	v_exp_f32_e32 v63, v1
	v_sub_f32_e32 v1, v238, v196
	v_add_f32_e32 v0, v59, v0
	v_exp_f32_e32 v64, v1
	v_sub_f32_e32 v1, v237, v196
	v_add_f32_e32 v0, v60, v0
	v_exp_f32_e32 v65, v1
	v_sub_f32_e32 v1, v236, v196
	v_add_f32_e32 v0, v61, v0
	v_exp_f32_e32 v66, v1
	v_sub_f32_e32 v1, v235, v196
	v_add_f32_e32 v0, v62, v0
	v_exp_f32_e32 v67, v1
	v_add_f32_e32 v0, v63, v0
	v_sub_f32_e32 v1, v81, v196
	v_add_f32_e32 v0, v64, v0
	v_exp_f32_e32 v68, v1
	v_sub_f32_e32 v1, v82, v196
	v_add_f32_e32 v0, v65, v0
	v_exp_f32_e32 v69, v1
	v_sub_f32_e32 v1, v83, v196
	v_add_f32_e32 v0, v66, v0
	v_exp_f32_e32 v70, v1
	v_sub_f32_e32 v1, v164, v196
	v_add_f32_e32 v0, v67, v0
	v_exp_f32_e32 v71, v1
	v_sub_f32_e32 v1, v165, v196
	v_exp_f32_e32 v197, v1
	v_sub_f32_e32 v1, v166, v196
	v_add_f32_e32 v0, v68, v0
	v_exp_f32_e32 v232, v1
	v_sub_f32_e32 v1, v167, v196
	v_add_f32_e32 v0, v69, v0
	v_exp_f32_e32 v233, v1
	v_sub_f32_e32 v1, v168, v196
	v_add_f32_e32 v0, v70, v0
	v_exp_f32_e32 v234, v1
	v_sub_f32_e32 v1, v72, v196
	v_add_f32_e32 v0, v71, v0
	v_exp_f32_e32 v235, v1
	v_sub_f32_e32 v1, v73, v196
	v_add_f32_e32 v0, v197, v0
	v_exp_f32_e32 v236, v1
	v_sub_f32_e32 v1, v74, v196
	v_add_f32_e32 v0, v232, v0
	v_exp_f32_e32 v237, v1
	v_sub_f32_e32 v1, v75, v196
	v_add_f32_e32 v0, v233, v0
	v_exp_f32_e32 v238, v1
	v_sub_f32_e32 v1, v76, v196
	v_add_f32_e32 v0, v234, v0
	v_exp_f32_e32 v239, v1
	v_sub_f32_e32 v1, v77, v196
	v_add_f32_e32 v0, v235, v0
	v_exp_f32_e32 v240, v1
	v_sub_f32_e32 v1, v78, v196
	v_add_f32_e32 v0, v236, v0
	v_exp_f32_e32 v241, v1
	v_sub_f32_e32 v1, v79, v196
	v_add_f32_e32 v0, v237, v0
	v_exp_f32_e32 v242, v1
	v_add_f32_e32 v0, v238, v0
	v_add_f32_e32 v0, v239, v0
	v_add_f32_e32 v0, v240, v0
	v_readlane_b32 s0, v245, 7
	v_add_f32_e32 v0, v241, v0
	s_add_i32 s2, s2, s0
	v_add_f32_e32 v243, v242, v0
	s_cmpk_gt_i32 s2, 0x5ff
	v_mov_b32_e32 v244, v243
	s_cselect_b64 s[70:71], -1, 0
	s_nop 0
	v_permlane32_swap_b32_e32 v243, v244
	s_and_b64 vcc, exec, s[70:71]
	s_mov_b32 s4, s85
	v_readlane_b32 s1, v245, 8
	s_cbranch_vccnz .LBB0_594
	s_ashr_i32 s92, s2, 9
	s_lshl_b32 s8, s92, 1
	s_lshr_b32 s1, 64, s8
	s_bfe_u32 s0, s2, 0x60003
	s_add_i32 s1, s1, -1
	s_sub_i32 s4, 6, s8
	s_and_b32 s10, s1, s0
	s_and_b32 s5, s2, 7
	s_lshr_b32 s94, s0, s4
	s_lshl_b32 s4, s10, 8
	s_add_i32 s9, s4, 0xffffff80
	s_lshl_b32 s0, s5, 8
	s_mov_b32 s1, s97
	s_cmp_lg_u32 s10, 0
	s_mov_b32 s95, s97
	v_lshl_add_u64 v[0:1], v[190:191], 0, s[0:1]
	s_cselect_b64 vcc, -1, 0
	s_cmp_eq_u32 s10, 0
	s_cbranch_scc1 .LBB0_588
	v_or_b32_e32 v2, s9, v198
	v_mov_b32_e32 v3, v80
	v_lshlrev_b64 v[2:3], s8, v[2:3]
	v_lshl_add_u64 v[2:3], v[2:3], 0, s[94:95]
	v_lshlrev_b64 v[2:3], 11, v[2:3]
	v_lshl_add_u64 v[2:3], v[0:1], 0, v[2:3]
	global_load_dwordx4 v[84:87], v[2:3], off
	v_cndmask_b32_e64 v2, 0, 1, vcc
	v_cmp_ne_u32_e64 s[0:1], 1, v2
	s_andn2_b64 vcc, exec, vcc
	s_cbranch_vccnz .LBB0_589
